# instruction-fetch alignment also on the hyena batch-pair loop, ph_post and rmsnorm row loop headers
# speedup vs baseline: 1.0035x; 1.0035x over previous
; __device__ __forceinline__ int otid() { int t = threadIdx.x; asm volatile("" : "+v"(t)); return t; }
; __device__ __forceinline__ uint4 ntld_u4(const void* p) { const ntu4_t v = __builtin_nontemporal_load((const ntu4_t*)p); return make_uint4(v.x, v.y, v.z, v.w); }
; __device__ void ph_rmsnorm_rows_b16(const bf16_t* __restrict__ hb, const float* __restrict__ g, bf16_t* __restrict__ out) {
;     const int tid = otid(); const int lane = tid & 63, wid = tid >> 6;
;     for (int row = blockIdx.x * 8 + wid; row < T_TOK; row += gridDim.x * 8) {
;         const size_t ro = (size_t)row * DM; uint4 w[2]; float v[2][8]; float ss = 0.f;
; #pragma unroll
;         for (int i = 0; i < 2; ++i) w[i] = ntld_u4(hb + ro + (lane + 64 * i) * 8);
; #pragma unroll
;         for (int i = 0; i < 2; ++i) { const unsigned ww[4] = {w[i].x, w[i].y, w[i].z, w[i].w};
; #pragma unroll
;             for (int k = 0; k < 4; ++k) { v[i][2 * k] = __uint_as_float(ww[k] << 16); v[i][2 * k + 1] = __uint_as_float(ww[k] & 0xffff0000u); ss += v[i][2 * k] * v[i][2 * k] + v[i][2 * k + 1] * v[i][2 * k + 1]; } }
;         ss = wave_sum(ss);
;         const float r = rsqrtf(ss * (1.0f / DM) + RMS_EPS);
;         float4 gaa[2], gbb[2];
; #pragma unroll
;         for (int i = 0; i < 2; ++i) { const int e0 = (lane + 64 * i) * 8; gaa[i] = *(const float4*)(g + e0); gbb[i] = *(const float4*)(g + e0 + 4); }
.LBB0_11:
	s_lshr_b32 s6, s28, 1
	v_writelane_b32 v255, s6, 50
	s_lshr_b64 s[30:31], s[28:29], 1
	s_andn2_b64 vcc, exec, s[10:11]
	v_writelane_b32 v255, s7, 51
	v_readlane_b32 s6, v252, 58
	v_writelane_b32 v255, s28, 52
	v_readlane_b32 s7, v252, 59
	s_nop 0
	v_writelane_b32 v255, s29, 53
	s_cbranch_vccnz .LBB0_149
	s_cmp_lg_u32 s28, 0
	s_cbranch_scc0 .LBB0_17
	s_waitcnt vmcnt(0)
	v_mov_b32_e32 v1, v195
	v_readlane_b32 s0, v252, 52
	v_ashrrev_i32_e32 v0, 6, v1
	s_nop 0
	v_add_u32_e32 v0, s0, v0
	s_mov_b32 s0, 0x8000
	v_cmp_gt_i32_e32 vcc, s0, v0
	s_and_saveexec_b64 s[14:15], vcc
	s_cbranch_execz .LBB0_16
	s_lshl_b32 s62, s28, 10
	v_readlane_b32 s40, v252, 2
	s_lshl_b64 s[0:1], s[62:63], 2
	v_readlane_b32 s48, v252, 10
	v_lshlrev_b32_e32 v1, 3, v1
	v_readlane_b32 s49, v252, 11
	s_add_u32 s0, s48, s0
	v_and_b32_e32 v1, 0x1f8, v1
	s_addc_u32 s1, s49, s1
	v_lshlrev_b32_e32 v192, 2, v1
	v_readlane_b32 s28, v255, 52
	v_lshl_add_u64 v[2:3], s[0:1], 0, v[192:193]
	v_lshlrev_b32_e32 v192, 1, v1
	v_readlane_b32 s29, v255, 53
	v_readlane_b32 s6, v252, 53
	v_lshl_add_u64 v[4:5], s[76:77], 0, v[192:193]
	v_lshl_add_u64 v[6:7], s[78:79], 0, v[192:193]
	s_mov_b64 s[10:11], 0
	v_readlane_b32 s41, v252, 3
	v_readlane_b32 s42, v252, 4
	v_readlane_b32 s43, v252, 5
	v_readlane_b32 s44, v252, 6
	v_readlane_b32 s45, v252, 7
	v_readlane_b32 s46, v252, 8
	v_readlane_b32 s47, v252, 9
	v_readlane_b32 s50, v252, 12
	v_readlane_b32 s51, v252, 13
	v_readlane_b32 s52, v252, 14
	v_readlane_b32 s53, v252, 15
	v_readlane_b32 s54, v252, 16
	v_readlane_b32 s55, v252, 17
	global_load_dwordx4 v[104:107], v[2:3], off offset:16
	global_load_dwordx4 v[108:111], v[2:3], off
	global_load_dwordx4 v[112:115], v[2:3], off offset:2064
	global_load_dwordx4 v[116:119], v[2:3], off offset:2048
	.p2align	6

; #define LAS __attribute__((address_space(3)))
; __device__ __forceinline__ cf twc(cf ws, int k16) { if (k16 == 0) return ws; if (k16 == 4) return cf{ws.y, -ws.x}; return cmul(ws, cf{c16(k16), -s16(k16)}); }
; template <int LR> __device__ __forceinline__ void dif_reg(cf (&x)[1 << LR], cf w) {
;     constexpr int R = 1 << LR; cf ws = w;
; #pragma unroll
;     for (int s = 0; s < LR; ++s) { const int half = R >> (s + 1);
; #pragma unroll
;         for (int m0 = 0; m0 < R; m0 += 2 * half)
; #pragma unroll
;             for (int mm = 0; mm < half; ++mm) { const int ia = m0 + mm, ib = ia + half; const cf a = x[ia], b = x[ib];
;                 x[ia] = cf{a.x + b.x, a.y + b.y}; const cf d{a.x - b.x, a.y - b.y};
;                 x[ib] = cmul(d, twc(ws, (mm << s) * (16 / R))); }
;         ws = cmul(ws, ws); }
; template <int LR, bool INV> __device__ __forceinline__ void fft_pass(ldsf2 buf, int base, int stride, int twi) {
;     constexpr int R = 1 << LR; cf x[R];
;     const v2f wv = ((ldsf2)((LAS unsigned char*)buf + 139264))[twi];
; #pragma unroll
;     for (int m = 0; m < R; ++m) { const v2f v = buf[base + m * stride]; x[m] = cf{v.x, v.y}; }
;     const cf w{wv.x, wv.y};
;     if (INV) dit_reg<LR>(x, w); else dif_reg<LR>(x, w);
; #pragma unroll
;     for (int m = 0; m < R; ++m) buf[base + m * stride] = mkv2(x[m].x, x[m].y);
; }
; __device__ __forceinline__ void fft_fwd_abc(ldsf2 buf) {
;     ...
;     for (int u = 0; u < 2; ++u) { const int j = l + 64 * u, o = j & 15, e0 = wv * 1024 + (j >> 4) * 128 + o; fft_pass<3, false>(buf, e0 + (e0 >> 4), 17, o * 64); }
.LBB0_344:
	v_or_b32_e32 v5, s0, v3
	ds_read_b64 v[14:15], v4
	v_lshlrev_b32_e32 v6, 3, v5
	v_ashrrev_i32_e32 v5, 1, v5
	v_add3_u32 v5, v2, v6, v5
	ds_read2_b64 v[6:9], v5 offset1:17
	ds_read2_b64 v[10:13], v5 offset0:34 offset1:51
	ds_read2_b64 v[24:27], v5 offset0:68 offset1:85
	ds_read2_b64 v[28:31], v5 offset0:102 offset1:119
	s_waitcnt lgkmcnt(4)
	v_pk_add_f32 v[32:33], v[14:15], v[14:15] op_sel:[0,1] op_sel_hi:[1,0] neg_lo:[0,0] neg_hi:[0,1]
	v_pk_mul_f32 v[38:39], v[14:15], v[14:15] op_sel:[1,1] op_sel_hi:[1,0]
	v_pk_mul_f32 v[34:35], v[32:33], s[16:17] op_sel:[0,0] op_sel_hi:[1,0]
	v_pk_fma_f32 v[38:39], v[14:15], v[14:15], v[38:39] op_sel:[0,0,0] op_sel_hi:[0,1,1] neg_lo:[0,0,1] neg_hi:[0,0,0]
	v_pk_mul_f32 v[36:37], v[32:33], s[16:17] op_sel:[1,0] op_sel_hi:[0,0] neg_lo:[0,0] neg_hi:[1,0]
	s_nop 0
	v_pk_mul_f32 v[40:41], v[38:39], v[38:39] op_sel:[1,1] op_sel_hi:[1,0]
	s_nop 0
	v_pk_fma_f32 v[40:41], v[38:39], v[38:39], v[40:41] op_sel:[0,0,0] op_sel_hi:[0,1,1] neg_lo:[0,0,1] neg_hi:[0,0,0]
	s_waitcnt lgkmcnt(0)
	v_pk_add_f32 v[42:43], v[6:7], v[24:25] neg_lo:[0,1] neg_hi:[0,1]
	v_pk_add_f32 v[44:45], v[8:9], v[26:27] neg_lo:[0,1] neg_hi:[0,1]
	v_pk_add_f32 v[46:47], v[10:11], v[28:29] neg_lo:[0,1] neg_hi:[0,1]
	v_pk_add_f32 v[48:49], v[12:13], v[30:31] neg_lo:[0,1] neg_hi:[0,1]
	v_pk_add_f32 v[6:7], v[6:7], v[24:25]
	v_pk_add_f32 v[8:9], v[8:9], v[26:27]
	v_pk_add_f32 v[10:11], v[10:11], v[28:29]
	v_pk_add_f32 v[12:13], v[12:13], v[30:31]
	v_pk_mul_f32 v[24:25], v[42:43], v[14:15] op_sel:[1,1] op_sel_hi:[1,0]
	v_pk_mul_f32 v[26:27], v[44:45], v[34:35] op_sel:[1,1] op_sel_hi:[1,0]
	v_pk_mul_f32 v[28:29], v[46:47], v[14:15] op_sel:[1,0] op_sel_hi:[1,1]
	v_pk_mul_f32 v[30:31], v[48:49], v[36:37] op_sel:[1,1] op_sel_hi:[1,0]
	v_pk_fma_f32 v[24:25], v[42:43], v[14:15], v[24:25] op_sel:[0,0,0] op_sel_hi:[0,1,1] neg_lo:[0,0,1] neg_hi:[0,0,0]
	v_pk_fma_f32 v[26:27], v[44:45], v[34:35], v[26:27] op_sel:[0,0,0] op_sel_hi:[0,1,1] neg_lo:[0,0,1] neg_hi:[0,0,0]
	v_pk_fma_f32 v[28:29], v[46:47], v[14:15], v[28:29] op_sel:[0,1,0] op_sel_hi:[0,0,1] neg_lo:[0,0,0] neg_hi:[0,1,0]
	v_pk_fma_f32 v[30:31], v[48:49], v[36:37], v[30:31] op_sel:[0,0,0] op_sel_hi:[0,1,1] neg_lo:[0,0,1] neg_hi:[0,0,0]
	v_pk_add_f32 v[42:43], v[6:7], v[10:11] neg_lo:[0,1] neg_hi:[0,1]
	v_pk_add_f32 v[44:45], v[8:9], v[12:13] neg_lo:[0,1] neg_hi:[0,1]
	v_pk_add_f32 v[46:47], v[24:25], v[28:29] neg_lo:[0,1] neg_hi:[0,1]
	v_pk_add_f32 v[48:49], v[26:27], v[30:31] neg_lo:[0,1] neg_hi:[0,1]
	v_pk_add_f32 v[6:7], v[6:7], v[10:11]
	v_pk_add_f32 v[8:9], v[8:9], v[12:13]
	v_pk_add_f32 v[24:25], v[24:25], v[28:29]
	v_pk_add_f32 v[26:27], v[26:27], v[30:31]
	v_pk_mul_f32 v[10:11], v[42:43], v[38:39] op_sel:[1,1] op_sel_hi:[1,0]
	v_pk_mul_f32 v[12:13], v[44:45], v[38:39] op_sel:[1,0] op_sel_hi:[1,1]
	v_pk_mul_f32 v[28:29], v[46:47], v[38:39] op_sel:[1,1] op_sel_hi:[1,0]
	v_pk_mul_f32 v[30:31], v[48:49], v[38:39] op_sel:[1,0] op_sel_hi:[1,1]
	v_pk_fma_f32 v[10:11], v[42:43], v[38:39], v[10:11] op_sel:[0,0,0] op_sel_hi:[0,1,1] neg_lo:[0,0,1] neg_hi:[0,0,0]
	v_pk_fma_f32 v[12:13], v[44:45], v[38:39], v[12:13] op_sel:[0,1,0] op_sel_hi:[0,0,1] neg_lo:[0,0,0] neg_hi:[0,1,0]
	v_pk_fma_f32 v[28:29], v[46:47], v[38:39], v[28:29] op_sel:[0,0,0] op_sel_hi:[0,1,1] neg_lo:[0,0,1] neg_hi:[0,0,0]
	v_pk_fma_f32 v[30:31], v[48:49], v[38:39], v[30:31] op_sel:[0,1,0] op_sel_hi:[0,0,1] neg_lo:[0,0,0] neg_hi:[0,1,0]
	v_pk_add_f32 v[42:43], v[6:7], v[8:9] neg_lo:[0,1] neg_hi:[0,1]
	v_pk_add_f32 v[44:45], v[10:11], v[12:13] neg_lo:[0,1] neg_hi:[0,1]
	v_pk_add_f32 v[46:47], v[24:25], v[26:27] neg_lo:[0,1] neg_hi:[0,1]
	v_pk_add_f32 v[48:49], v[28:29], v[30:31] neg_lo:[0,1] neg_hi:[0,1]
	v_pk_add_f32 v[6:7], v[6:7], v[8:9]
	v_pk_add_f32 v[10:11], v[10:11], v[12:13]
	v_pk_add_f32 v[24:25], v[24:25], v[26:27]
	v_pk_add_f32 v[28:29], v[28:29], v[30:31]
	v_pk_mul_f32 v[8:9], v[42:43], v[40:41] op_sel:[1,1] op_sel_hi:[1,0]
	v_pk_mul_f32 v[12:13], v[44:45], v[40:41] op_sel:[1,1] op_sel_hi:[1,0]
	v_pk_mul_f32 v[26:27], v[46:47], v[40:41] op_sel:[1,1] op_sel_hi:[1,0]
	v_pk_mul_f32 v[30:31], v[48:49], v[40:41] op_sel:[1,1] op_sel_hi:[1,0]
	v_pk_fma_f32 v[8:9], v[42:43], v[40:41], v[8:9] op_sel:[0,0,0] op_sel_hi:[0,1,1] neg_lo:[0,0,1] neg_hi:[0,0,0]
	v_pk_fma_f32 v[12:13], v[44:45], v[40:41], v[12:13] op_sel:[0,0,0] op_sel_hi:[0,1,1] neg_lo:[0,0,1] neg_hi:[0,0,0]
	v_pk_fma_f32 v[26:27], v[46:47], v[40:41], v[26:27] op_sel:[0,0,0] op_sel_hi:[0,1,1] neg_lo:[0,0,1] neg_hi:[0,0,0]
	v_pk_fma_f32 v[30:31], v[48:49], v[40:41], v[30:31] op_sel:[0,0,0] op_sel_hi:[0,1,1] neg_lo:[0,0,1] neg_hi:[0,0,0]
	ds_write2_b64 v5, v[6:7], v[8:9] offset1:17
	ds_write2_b64 v5, v[10:11], v[12:13] offset0:34 offset1:51
	ds_write2_b64 v5, v[24:25], v[26:27] offset0:68 offset1:85
	ds_write2_b64 v5, v[28:29], v[30:31] offset0:102 offset1:119
	s_movk_i32 s0, 0x200
	s_and_b64 vcc, exec, s[10:11]
	s_mov_b64 s[10:11], 0
	s_cbranch_vccnz .LBB0_344
; __device__ __forceinline__ cf twc(cf ws, int k16) { if (k16 == 0) return ws; if (k16 == 4) return cf{ws.y, -ws.x}; return cmul(ws, cf{c16(k16), -s16(k16)}); }
; template <int LR> __device__ __forceinline__ void dif_reg(cf (&x)[1 << LR], cf w) {
;     constexpr int R = 1 << LR; cf ws = w;
; #pragma unroll
;     for (int s = 0; s < LR; ++s) { const int half = R >> (s + 1);
; #pragma unroll
;         for (int m0 = 0; m0 < R; m0 += 2 * half)
; #pragma unroll
;             for (int mm = 0; mm < half; ++mm) { const int ia = m0 + mm, ib = ia + half; const cf a = x[ia], b = x[ib];
;                 x[ia] = cf{a.x + b.x, a.y + b.y}; const cf d{a.x - b.x, a.y - b.y};
;                 x[ib] = cmul(d, twc(ws, (mm << s) * (16 / R))); }
;         ws = cmul(ws, ws); }
; __device__ __forceinline__ void make_spec(ldsf2 buf, LAS unsigned* spec, const float* __restrict__ kfrow) {
;     ...
;     cf x[16];
; #pragma unroll
;     for (int m = 0; m < 16; ++m) { const v2f v = buf[tid * 17 + m]; x[m] = cf{v.x, v.y}; }
;     dif_reg<4>(x, cf{1.0f, 0.0f});
; #pragma unroll
;     for (int m = 0; m < 16; ++m) { h2_t hv; hv.x = (_Float16)x[m].x; hv.y = (_Float16)x[m].y; spec[tid * 17 + m] = __builtin_bit_cast(unsigned, hv); }
	s_waitcnt lgkmcnt(0)
	ds_read2_b64 v[2:5], v1 offset1:1
	ds_read2_b64 v[6:9], v1 offset0:2 offset1:3
	ds_read2_b64 v[10:13], v1 offset0:4 offset1:5
	ds_read2_b64 v[24:27], v1 offset0:6 offset1:7
	ds_read2_b64 v[28:31], v1 offset0:8 offset1:9
	ds_read2_b64 v[32:35], v1 offset0:10 offset1:11
	ds_read2_b64 v[36:39], v1 offset0:12 offset1:13
	ds_read2_b64 v[40:43], v1 offset0:14 offset1:15
	s_movk_i32 s0, 0x44
	v_mul_lo_u32 v0, v0, s0
	v_add_u32_e32 v0, 0, v0
	v_add_u32_e32 v70, 0x19800, v0
	s_waitcnt lgkmcnt(3)
	v_pk_add_f32 v[0:1], v[2:3], v[28:29]
	v_pk_add_f32 v[14:15], v[4:5], v[30:31]
	s_waitcnt lgkmcnt(2)
	v_pk_add_f32 v[44:45], v[6:7], v[32:33]
	v_pk_add_f32 v[46:47], v[8:9], v[34:35]
	s_waitcnt lgkmcnt(1)
	v_pk_add_f32 v[48:49], v[10:11], v[36:37]
	v_pk_add_f32 v[50:51], v[12:13], v[38:39]
	s_waitcnt lgkmcnt(0)
	v_pk_add_f32 v[52:53], v[24:25], v[40:41]
	v_pk_add_f32 v[54:55], v[26:27], v[42:43]
	v_pk_add_f32 v[56:57], v[0:1], v[48:49]
	v_pk_add_f32 v[58:59], v[14:15], v[50:51]
	v_pk_add_f32 v[60:61], v[44:45], v[52:53]
	v_pk_add_f32 v[62:63], v[46:47], v[54:55]
	v_pk_add_f32 v[64:65], v[56:57], v[60:61]
	v_pk_add_f32 v[66:67], v[58:59], v[62:63]
	v_pk_add_f32 v[56:57], v[56:57], v[60:61] neg_lo:[0,1] neg_hi:[0,1]
	v_pk_add_f32 v[68:69], v[64:65], v[66:67]
	v_pk_add_f32 v[64:65], v[64:65], v[66:67] neg_lo:[0,1] neg_hi:[0,1]
	v_cvt_pk_f16_f32 v71, v68, v69
	v_pk_mul_f32 v[66:67], v[64:65], 0 op_sel_hi:[1,0]
	v_pk_mul_f32 v[60:61], v[56:57], 0 op_sel_hi:[1,0]
	v_pk_add_f32 v[68:69], v[64:65], v[66:67] op_sel:[0,1] op_sel_hi:[1,0] neg_lo:[0,1] neg_hi:[0,1]
	v_pk_add_f32 v[64:65], v[64:65], v[66:67] op_sel:[0,1] op_sel_hi:[1,0]
	v_pk_add_f32 v[0:1], v[0:1], v[48:49] neg_lo:[0,1] neg_hi:[0,1]
	v_cvt_pk_f16_f32 v64, v68, v65
	ds_write2_b32 v70, v71, v64 offset1:1
	v_pk_add_f32 v[64:65], v[56:57], v[60:61] op_sel:[0,1] op_sel_hi:[1,0] neg_lo:[0,1] neg_hi:[0,1]
	v_pk_add_f32 v[56:57], v[56:57], v[60:61] op_sel:[0,1] op_sel_hi:[1,0]
	v_pk_mul_f32 v[48:49], v[0:1], 0 op_sel_hi:[1,0]
	v_mov_b32_e32 v65, v57
	v_pk_add_f32 v[56:57], v[58:59], v[62:63] neg_lo:[0,1] neg_hi:[0,1]
	s_mov_b32 s0, s87
	v_pk_fma_f32 v[58:59], v[56:57], 0, v[56:57] op_sel:[0,0,1] op_sel_hi:[1,0,0]
	v_pk_fma_f32 v[56:57], v[56:57], 0, v[56:57] op_sel:[0,0,1] op_sel_hi:[1,0,0] neg_lo:[0,0,1] neg_hi:[0,0,1]
	s_mov_b32 s1, s16
	v_mov_b32_e32 v59, v57
	v_pk_add_f32 v[56:57], v[64:65], v[58:59]
	s_mov_b32 s17, s87
	v_cvt_pk_f16_f32 v62, v56, v57
	v_pk_add_f32 v[56:57], v[64:65], v[58:59] neg_lo:[0,1] neg_hi:[0,1]
	s_mov_b32 s10, s5
	v_pk_mul_f32 v[58:59], v[56:57], 0 op_sel_hi:[1,0]
	s_mov_b32 s14, s13
	v_pk_add_f32 v[60:61], v[56:57], v[58:59] op_sel:[0,1] op_sel_hi:[1,0] neg_lo:[0,1] neg_hi:[0,1]
	v_pk_add_f32 v[56:57], v[56:57], v[58:59] op_sel:[0,1] op_sel_hi:[1,0]
	v_mov_b32_e32 v58, v51
	v_cvt_pk_f16_f32 v56, v60, v57
	ds_write2_b32 v70, v62, v56 offset0:2 offset1:3
	v_pk_add_f32 v[56:57], v[0:1], v[48:49] op_sel:[0,1] op_sel_hi:[1,0] neg_lo:[0,1] neg_hi:[0,1]
	v_pk_add_f32 v[0:1], v[0:1], v[48:49] op_sel:[0,1] op_sel_hi:[1,0]
	v_mov_b32_e32 v48, v54
	v_mov_b32_e32 v57, v1
	v_pk_add_f32 v[0:1], v[44:45], v[52:53] neg_lo:[0,1] neg_hi:[0,1]
	v_mov_b32_e32 v49, v51
	v_pk_fma_f32 v[44:45], v[0:1], 0, v[0:1] op_sel:[0,0,1] op_sel_hi:[1,0,0]
	v_pk_fma_f32 v[0:1], v[0:1], 0, v[0:1] op_sel:[0,0,1] op_sel_hi:[1,0,0] neg_lo:[0,0,1] neg_hi:[0,0,1]
	v_mov_b32_e32 v52, v50
	v_mov_b32_e32 v45, v1
	v_mov_b32_e32 v0, v46
	v_mov_b32_e32 v1, v15
	v_pk_add_f32 v[0:1], v[0:1], v[48:49] neg_lo:[0,1] neg_hi:[0,1]
	v_mov_b32_e32 v48, v14
	v_mov_b32_e32 v49, v46
	v_mov_b32_e32 v53, v54
	v_pk_add_f32 v[48:49], v[48:49], v[52:53] neg_lo:[0,1] neg_hi:[0,1]
	v_mov_b32_e32 v52, v15
	v_mov_b32_e32 v53, v47
	v_mov_b32_e32 v59, v55
	v_pk_mov_b32 v[14:15], v[46:47], v[14:15] op_sel:[1,0]
	v_pk_mov_b32 v[46:47], v[54:55], v[50:51] op_sel:[1,0]
	v_pk_add_f32 v[52:53], v[52:53], v[58:59] neg_lo:[0,1] neg_hi:[0,1]
	v_pk_add_f32 v[14:15], v[14:15], v[46:47] neg_lo:[0,1] neg_hi:[0,1]
	v_pk_mul_f32 v[46:47], v[52:53], s[16:17]
	v_pk_mul_f32 v[14:15], v[14:15], s[0:1]
	s_mov_b32 s15, s4
	v_pk_fma_f32 v[0:1], v[0:1], s[0:1], v[14:15] neg_lo:[0,0,1] neg_hi:[0,0,1]
	v_pk_fma_f32 v[14:15], v[48:49], s[16:17], v[46:47]
	v_pk_add_f32 v[46:47], v[56:57], v[44:45]
	v_pk_add_f32 v[48:49], v[14:15], v[0:1]
	v_pk_add_f32 v[44:45], v[56:57], v[44:45] neg_lo:[0,1] neg_hi:[0,1]
	v_pk_add_f32 v[50:51], v[46:47], v[48:49]
	v_pk_add_f32 v[46:47], v[46:47], v[48:49] neg_lo:[0,1] neg_hi:[0,1]
	v_cvt_pk_f16_f32 v52, v50, v51
	v_pk_mul_f32 v[48:49], v[46:47], 0 op_sel_hi:[1,0]
	s_mov_b32 s35, s5
	v_pk_add_f32 v[50:51], v[46:47], v[48:49] op_sel:[0,1] op_sel_hi:[1,0] neg_lo:[0,1] neg_hi:[0,1]
	v_pk_add_f32 v[46:47], v[46:47], v[48:49] op_sel:[0,1] op_sel_hi:[1,0]
	s_mov_b32 s48, 0
	v_cvt_pk_f16_f32 v46, v50, v47
	ds_write2_b32 v70, v52, v46 offset0:4 offset1:5
	v_pk_mul_f32 v[46:47], v[44:45], 0 op_sel_hi:[1,0]
	s_mov_b32 s49, s48
	v_pk_add_f32 v[48:49], v[44:45], v[46:47] op_sel:[0,1] op_sel_hi:[1,0] neg_lo:[0,1] neg_hi:[0,1]
	v_pk_add_f32 v[44:45], v[44:45], v[46:47] op_sel:[0,1] op_sel_hi:[1,0]
	s_mov_b32 s50, s48
	v_mov_b32_e32 v49, v45
	v_mov_b32_e32 v44, v14
	v_mov_b32_e32 v45, v1
	v_mov_b32_e32 v1, v15
	v_pk_add_f32 v[0:1], v[44:45], v[0:1] neg_lo:[0,1] neg_hi:[0,1]
	s_mov_b32 s51, s48
	v_pk_fma_f32 v[14:15], v[0:1], 0, v[0:1] op_sel:[0,0,1] op_sel_hi:[1,0,0]
	v_pk_fma_f32 v[0:1], v[0:1], 0, v[0:1] op_sel:[0,0,1] op_sel_hi:[1,0,0] neg_lo:[0,0,1] neg_hi:[0,0,1]
	s_mov_b32 s53, s48
	v_mov_b32_e32 v15, v1
	v_pk_add_f32 v[0:1], v[48:49], v[14:15]
	s_nop 0
	v_cvt_pk_f16_f32 v46, v0, v1
	v_pk_add_f32 v[0:1], v[48:49], v[14:15] neg_lo:[0,1] neg_hi:[0,1]
; __device__ __forceinline__ cf twc(cf ws, int k16) { if (k16 == 0) return ws; if (k16 == 4) return cf{ws.y, -ws.x}; return cmul(ws, cf{c16(k16), -s16(k16)}); }
; template <int LR> __device__ __forceinline__ void dif_reg(cf (&x)[1 << LR], cf w) {
;     constexpr int R = 1 << LR; cf ws = w;
; #pragma unroll
;     for (int s = 0; s < LR; ++s) { const int half = R >> (s + 1);
; #pragma unroll
;         for (int m0 = 0; m0 < R; m0 += 2 * half)
; #pragma unroll
;             for (int mm = 0; mm < half; ++mm) { const int ia = m0 + mm, ib = ia + half; const cf a = x[ia], b = x[ib];
;                 x[ia] = cf{a.x + b.x, a.y + b.y}; const cf d{a.x - b.x, a.y - b.y};
;                 x[ib] = cmul(d, twc(ws, (mm << s) * (16 / R))); }
;         ws = cmul(ws, ws); }
; __device__ __forceinline__ void make_spec(ldsf2 buf, LAS unsigned* spec, const float* __restrict__ kfrow) {
;     ...
;     cf x[16];
; #pragma unroll
;     for (int m = 0; m < 16; ++m) { const v2f v = buf[tid * 17 + m]; x[m] = cf{v.x, v.y}; }
;     dif_reg<4>(x, cf{1.0f, 0.0f});
; #pragma unroll
;     for (int m = 0; m < 16; ++m) { h2_t hv; hv.x = (_Float16)x[m].x; hv.y = (_Float16)x[m].y; spec[tid * 17 + m] = __builtin_bit_cast(unsigned, hv); }
	s_nop 0
	v_pk_mul_f32 v[14:15], v[0:1], 0 op_sel_hi:[1,0]
	s_nop 0
	v_pk_add_f32 v[44:45], v[0:1], v[14:15] op_sel:[0,1] op_sel_hi:[1,0] neg_lo:[0,1] neg_hi:[0,1]
	v_pk_add_f32 v[0:1], v[0:1], v[14:15] op_sel:[0,1] op_sel_hi:[1,0]
	s_nop 0
	v_cvt_pk_f16_f32 v0, v44, v1
	ds_write2_b32 v70, v46, v0 offset0:6 offset1:7
	v_pk_add_f32 v[0:1], v[2:3], v[28:29] neg_lo:[0,1] neg_hi:[0,1]
	s_nop 0
	v_pk_mul_f32 v[2:3], v[0:1], 0 op_sel_hi:[1,0]
	s_nop 0
	v_pk_add_f32 v[14:15], v[0:1], v[2:3] op_sel:[0,1] op_sel_hi:[1,0] neg_lo:[0,1] neg_hi:[0,1]
	v_pk_add_f32 v[0:1], v[0:1], v[2:3] op_sel:[0,1] op_sel_hi:[1,0]
	v_pk_add_f32 v[2:3], v[4:5], v[30:31] neg_lo:[0,1] neg_hi:[0,1]
	v_pk_mov_b32 v[0:1], v[0:1], v[14:15] op_sel:[1,0]
	v_pk_mul_f32 v[4:5], v[2:3], s[4:5] op_sel_hi:[1,0]
	s_nop 0
	v_pk_fma_f32 v[14:15], v[2:3], s[10:11], v[4:5] op_sel:[0,0,1] op_sel_hi:[1,0,0]
	v_pk_fma_f32 v[2:3], v[2:3], s[10:11], v[4:5] op_sel:[0,0,1] op_sel_hi:[1,0,0] neg_lo:[1,0,0] neg_hi:[1,0,0]
	v_pk_add_f32 v[4:5], v[8:9], v[34:35] neg_lo:[0,1] neg_hi:[0,1]
	v_mov_b32_e32 v34, v40
	v_pk_mul_f32 v[8:9], v[4:5], s[10:11] op_sel_hi:[1,0]
	v_mov_b32_e32 v35, v32
	v_pk_fma_f32 v[28:29], v[4:5], s[4:5], v[8:9] op_sel:[0,0,1] op_sel_hi:[1,0,0]
	v_pk_fma_f32 v[4:5], v[4:5], s[4:5], v[8:9] op_sel:[0,0,1] op_sel_hi:[1,0,0] neg_lo:[1,0,0] neg_hi:[1,0,0]
	v_pk_add_f32 v[8:9], v[10:11], v[36:37] neg_lo:[0,1] neg_hi:[0,1]
	v_mov_b32_e32 v36, v41
	v_pk_mul_f32 v[10:11], v[8:9], 0 op_sel_hi:[1,0]
	v_mov_b32_e32 v37, v33
	v_pk_add_f32 v[30:31], v[10:11], v[8:9] op_sel:[1,0] op_sel_hi:[0,1]
	v_pk_add_f32 v[8:9], v[10:11], v[8:9] op_sel:[1,0] op_sel_hi:[0,1] neg_lo:[0,1] neg_hi:[0,1]
	v_pk_add_f32 v[10:11], v[12:13], v[38:39] neg_lo:[0,1] neg_hi:[0,1]
	v_mov_b32_e32 v9, v31
	v_pk_mul_f32 v[12:13], v[10:11], s[10:11] op_sel_hi:[1,0]
	v_pk_mov_b32 v[30:31], v[32:33], v[40:41] op_sel:[1,0]
	v_pk_fma_f32 v[10:11], v[10:11], s[14:15], v[12:13] op_sel:[0,0,1] op_sel_hi:[1,1,0] neg_lo:[0,0,1] neg_hi:[0,0,1]
	v_pk_mov_b32 v[12:13], v[6:7], v[24:25] op_sel:[1,0]
	v_mov_b32_e32 v33, v41
	v_pk_add_f32 v[12:13], v[12:13], v[30:31] neg_lo:[0,1] neg_hi:[0,1]
	v_mov_b32_e32 v30, v24
	v_mov_b32_e32 v31, v6
	v_pk_add_f32 v[30:31], v[30:31], v[34:35] neg_lo:[0,1] neg_hi:[0,1]
	v_mov_b32_e32 v34, v25
	v_mov_b32_e32 v35, v7
	v_mov_b32_e32 v7, v25
	v_pk_add_f32 v[34:35], v[34:35], v[36:37] neg_lo:[0,1] neg_hi:[0,1]
	v_pk_add_f32 v[6:7], v[6:7], v[32:33] neg_lo:[0,1] neg_hi:[0,1]
	v_pk_mul_f32 v[24:25], v[34:35], s[0:1]
	v_pk_mul_f32 v[6:7], v[6:7], s[16:17]
	v_mov_b32_e32 v3, v15
	v_pk_fma_f32 v[6:7], v[12:13], s[16:17], v[6:7] neg_lo:[0,0,1] neg_hi:[0,0,1]
	v_pk_fma_f32 v[12:13], v[30:31], s[0:1], v[24:25]
	v_pk_add_f32 v[24:25], v[26:27], v[42:43] neg_lo:[0,1] neg_hi:[0,1]
	v_mov_b32_e32 v28, v4
	v_pk_mul_f32 v[26:27], v[24:25], s[4:5] op_sel_hi:[1,0]
	v_pk_add_f32 v[30:31], v[2:3], v[10:11]
	v_pk_fma_f32 v[24:25], v[24:25], s[34:35], v[26:27] op_sel:[0,0,1] op_sel_hi:[1,1,0] neg_lo:[0,0,1] neg_hi:[0,0,1]
	v_pk_add_f32 v[26:27], v[0:1], v[8:9]
	v_pk_add_f32 v[32:33], v[12:13], v[6:7]
	v_pk_add_f32 v[34:35], v[28:29], v[24:25]
	v_pk_add_f32 v[36:37], v[26:27], v[32:33]
	v_pk_add_f32 v[38:39], v[30:31], v[34:35]
	v_pk_add_f32 v[26:27], v[26:27], v[32:33] neg_lo:[0,1] neg_hi:[0,1]
	v_pk_add_f32 v[40:41], v[36:37], v[38:39]
	v_pk_add_f32 v[36:37], v[36:37], v[38:39] neg_lo:[0,1] neg_hi:[0,1]
	v_pk_mov_b32 v[40:41], v[40:41], v[40:41] op_sel:[1,0]
	v_pk_mul_f32 v[38:39], v[36:37], 0 op_sel_hi:[1,0]
	v_cvt_pk_f16_f32 v3, v40, v41
	v_pk_add_f32 v[40:41], v[36:37], v[38:39] op_sel:[0,1] op_sel_hi:[1,0] neg_lo:[0,1] neg_hi:[0,1]
	v_pk_add_f32 v[36:37], v[36:37], v[38:39] op_sel:[0,1] op_sel_hi:[1,0]
	v_pk_mul_f32 v[32:33], v[26:27], 0 op_sel_hi:[1,0]
	v_pk_mov_b32 v[36:37], v[40:41], v[36:37] op_sel:[1,0]
	v_pk_add_f32 v[30:31], v[30:31], v[34:35] neg_lo:[0,1] neg_hi:[0,1]
	v_cvt_pk_f16_f32 v28, v36, v37
	v_pk_add_f32 v[36:37], v[26:27], v[32:33] op_sel:[0,1] op_sel_hi:[1,0] neg_lo:[0,1] neg_hi:[0,1]
	v_pk_add_f32 v[26:27], v[26:27], v[32:33] op_sel:[0,1] op_sel_hi:[1,0]
	v_pk_mul_f32 v[32:33], v[30:31], 0 op_sel_hi:[1,0]
	v_pk_mov_b32 v[26:27], v[36:37], v[26:27] op_sel:[1,0]
	v_pk_add_f32 v[34:35], v[32:33], v[30:31] op_sel:[1,0] op_sel_hi:[0,1]
	v_pk_add_f32 v[30:31], v[32:33], v[30:31] op_sel:[1,0] op_sel_hi:[0,1] neg_lo:[0,1] neg_hi:[0,1]
	v_mov_b32_e32 v35, v31
	v_pk_add_f32 v[30:31], v[26:27], v[34:35]
	v_pk_add_f32 v[26:27], v[26:27], v[34:35] neg_lo:[0,1] neg_hi:[0,1]
	ds_write2_b32 v70, v3, v28 offset0:8 offset1:9
	v_cvt_pk_f16_f32 v3, v30, v31
	v_pk_mul_f32 v[30:31], v[26:27], 0 op_sel_hi:[1,0]
	v_pk_add_f32 v[0:1], v[0:1], v[8:9] neg_lo:[0,1] neg_hi:[0,1]
	v_pk_add_f32 v[32:33], v[26:27], v[30:31] op_sel:[0,1] op_sel_hi:[1,0] neg_lo:[0,1] neg_hi:[0,1]
	v_pk_add_f32 v[26:27], v[26:27], v[30:31] op_sel:[0,1] op_sel_hi:[1,0]
	v_pk_mul_f32 v[8:9], v[0:1], 0 op_sel_hi:[1,0]
	v_cvt_pk_f16_f32 v26, v32, v27
	ds_write2_b32 v70, v3, v26 offset0:10 offset1:11
	v_pk_add_f32 v[26:27], v[0:1], v[8:9] op_sel:[0,1] op_sel_hi:[1,0] neg_lo:[0,1] neg_hi:[0,1]
	v_pk_add_f32 v[0:1], v[0:1], v[8:9] op_sel:[0,1] op_sel_hi:[1,0]
	v_pk_mov_b32 v[8:9], v[12:13], v[6:7] op_sel:[1,0]
	v_pk_mov_b32 v[6:7], v[6:7], v[12:13] op_sel:[1,0]
	v_mov_b32_e32 v3, v29
	v_pk_add_f32 v[6:7], v[8:9], v[6:7] neg_lo:[0,1] neg_hi:[0,1]
	v_pk_mov_b32 v[4:5], v[14:15], v[4:5] op_sel:[1,0]
	v_pk_fma_f32 v[8:9], v[6:7], 0, v[6:7] op_sel:[0,0,1] op_sel_hi:[1,0,0]
	v_pk_fma_f32 v[6:7], v[6:7], 0, v[6:7] op_sel:[0,0,1] op_sel_hi:[1,0,0] neg_lo:[0,0,1] neg_hi:[0,0,1]
	v_pk_mov_b32 v[0:1], v[26:27], v[0:1] op_sel:[1,0]
	v_mov_b32_e32 v9, v7
; __device__ __forceinline__ void lds_barrier() { asm volatile("s_waitcnt lgkmcnt(0)\n\ts_barrier" ::: "memory"); }
; __device__ __forceinline__ void make_spec(ldsf2 buf, LAS unsigned* spec, const float* __restrict__ kfrow) {
;     ...
;     for (int m = 0; m < 16; ++m) { h2_t hv; hv.x = (_Float16)x[m].x; hv.y = (_Float16)x[m].y; spec[tid * 17 + m] = __builtin_bit_cast(unsigned, hv); }
;     lds_barrier();
; __device__ void ph_hyena_fft(const Params& P, int j, const bf16_t* __restrict__ projAT, const float* __restrict__ kf, bf16_t* __restrict__ yaT, unsigned char* lds_raw) {
;     ...
;         const float wv0 = cw[c], wv1 = cw[3072 + c], wv2 = cw[6144 + c], bv = cb[c];
;         const float wa0 = cw[1024 + c], wa1 = cw[3072 + 1024 + c], wa2 = cw[6144 + 1024 + c], ba = cb[1024 + c];
;         const float wb0 = cw[2048 + c], wb1 = cw[3072 + 2048 + c], wb2 = cw[6144 + 2048 + c], bb = cb[2048 + c];
;         const float sk0 = skip[c], sk1 = skip[1024 + c];
;         const bf16_t* vrow = projAT + (size_t)c * T_TOK; const bf16_t* x1row = projAT + (size_t)(1024 + c) * T_TOK;
;         const bf16_t* x2row = projAT + (size_t)(2048 + c) * T_TOK; const bf16_t* grow = projAT + (size_t)(3072 + c) * T_TOK;
; #pragma unroll 1
;         for (int bp = 0; bp < 4; ++bp) {
;             const size_t o0 = (size_t)(2 * bp) * SEQ, o1 = o0 + SEQ;
	v_mov_b32_e32 v6, v10
	v_mov_b32_e32 v7, v25
	v_pk_add_f32 v[2:3], v[2:3], v[6:7] neg_lo:[0,1] neg_hi:[0,1]
	v_pk_mov_b32 v[6:7], v[10:11], v[24:25] op_sel:[1,0]
	v_pk_mul_f32 v[2:3], v[2:3], s[16:17]
	v_pk_add_f32 v[4:5], v[4:5], v[6:7] neg_lo:[0,1] neg_hi:[0,1]
	s_lshl_b64 s[0:1], s[46:47], 2
	v_pk_fma_f32 v[6:7], v[4:5], s[16:17], v[2:3] neg_lo:[1,0,0] neg_hi:[1,0,0]
	v_pk_fma_f32 v[2:3], v[4:5], s[16:17], v[2:3]
	v_pk_mov_b32 v[10:11], v[6:7], v[6:7] op_sel:[1,0]
	v_pk_add_f32 v[4:5], v[0:1], v[8:9]
	v_pk_add_f32 v[6:7], v[2:3], v[6:7] op_sel:[0,1] op_sel_hi:[1,0]
	v_pk_add_f32 v[0:1], v[0:1], v[8:9] neg_lo:[0,1] neg_hi:[0,1]
	v_pk_add_f32 v[12:13], v[4:5], v[6:7]
	v_pk_add_f32 v[4:5], v[4:5], v[6:7] neg_lo:[0,1] neg_hi:[0,1]
	v_cvt_pk_f16_f32 v14, v12, v13
	v_pk_mul_f32 v[6:7], v[4:5], 0 op_sel_hi:[1,0]
	s_add_u32 s14, s38, s0
	v_pk_add_f32 v[12:13], v[4:5], v[6:7] op_sel:[0,1] op_sel_hi:[1,0] neg_lo:[0,1] neg_hi:[0,1]
	v_pk_add_f32 v[4:5], v[4:5], v[6:7] op_sel:[0,1] op_sel_hi:[1,0]
	s_addc_u32 s15, s39, s1
	v_cvt_pk_f16_f32 v4, v12, v5
	ds_write2_b32 v70, v14, v4 offset0:12 offset1:13
	v_pk_mul_f32 v[4:5], v[0:1], 0 op_sel_hi:[1,0]
	s_lshl_b64 s[10:11], s[46:47], 16
	v_pk_add_f32 v[6:7], v[0:1], v[4:5] op_sel:[0,1] op_sel_hi:[1,0] neg_lo:[0,1] neg_hi:[0,1]
	v_pk_add_f32 v[0:1], v[0:1], v[4:5] op_sel:[0,1] op_sel_hi:[1,0]
	s_add_u32 s26, s54, s0
	v_mov_b32_e32 v7, v1
	v_mov_b32_e32 v0, v2
	v_mov_b32_e32 v1, v11
	v_mov_b32_e32 v11, v3
	v_pk_add_f32 v[0:1], v[0:1], v[10:11] neg_lo:[0,1] neg_hi:[0,1]
	s_addc_u32 s27, s55, s1
	v_pk_fma_f32 v[2:3], v[0:1], 0, v[0:1] op_sel:[0,0,1] op_sel_hi:[1,0,0]
	v_pk_fma_f32 v[0:1], v[0:1], 0, v[0:1] op_sel:[0,0,1] op_sel_hi:[1,0,0] neg_lo:[0,0,1] neg_hi:[0,0,1]
	s_add_u32 s0, s56, s0
	v_mov_b32_e32 v3, v1
	v_pk_add_f32 v[0:1], v[6:7], v[2:3]
	s_addc_u32 s1, s57, s1
	v_cvt_pk_f16_f32 v8, v0, v1
	v_pk_add_f32 v[0:1], v[6:7], v[2:3] neg_lo:[0,1] neg_hi:[0,1]
	s_nop 0
	v_pk_mul_f32 v[2:3], v[0:1], 0 op_sel_hi:[1,0]
	s_nop 0
	v_pk_add_f32 v[4:5], v[0:1], v[2:3] op_sel:[0,1] op_sel_hi:[1,0] neg_lo:[0,1] neg_hi:[0,1]
	v_pk_add_f32 v[0:1], v[0:1], v[2:3] op_sel:[0,1] op_sel_hi:[1,0]
	s_nop 0
	v_cvt_pk_f16_f32 v0, v4, v1
	ds_write2_b32 v70, v8, v0 offset0:14 offset1:15
	s_waitcnt lgkmcnt(0)
	s_barrier
	v_mov_b32_e32 v0, 0x3000
	global_load_dword v25, v193, s[14:15]
	global_load_dword v24, v0, s[14:15]
	v_mov_b32_e32 v0, 0x6000
	global_load_dword v26, v0, s[14:15]
	v_mov_b32_e32 v0, 0x7000
	global_load_dword v28, v193, s[26:27]
	global_load_dword v30, v231, s[14:15]
	global_load_dword v32, v230, s[14:15]
	global_load_dword v34, v0, s[14:15]
	global_load_dword v36, v231, s[26:27]
	global_load_dword v39, v238, s[14:15]
	v_mov_b32_e32 v0, 0x5000
	global_load_dword v38, v0, s[14:15]
	v_mov_b32_e32 v0, 0x8000
	global_load_dword v40, v0, s[14:15]
	global_load_dword v42, v238, s[26:27]
	global_load_dword v44, v193, s[0:1]
	global_load_dword v46, v231, s[0:1]
	s_lshl_b64 s[0:1], s[6:7], 1
	v_readlane_b32 s14, v252, 36
	v_readlane_b32 s15, v252, 37
	s_add_u32 s47, s14, s0
	s_addc_u32 s58, s15, s1
	s_lshl_b64 s[6:7], s[30:31], 16
	s_add_u32 s59, s14, s6
	s_addc_u32 s60, s15, s7
	s_add_u32 s6, s14, s10
	s_addc_u32 s7, s15, s11
	s_add_u32 s61, s6, 0x8000000
	s_addc_u32 s52, s7, 0
	v_lshl_add_u64 v[0:1], v[18:19], 0, s[10:11]
	s_mov_b64 s[6:7], 0xc000000
	v_lshl_add_u64 v[48:49], v[0:1], 0, s[6:7]
	v_lshl_add_u64 v[50:51], v[20:21], 0, s[0:1]
	s_waitcnt vmcnt(13)
	v_mov_b32_e32 v58, v25
	v_mov_b32_e32 v59, v25
	s_waitcnt vmcnt(12)
	v_mov_b32_e32 v60, v24
	s_waitcnt vmcnt(10)
	v_mov_b32_e32 v29, v28
	v_mov_b32_e32 v27, v26
	s_waitcnt vmcnt(6)
	v_mov_b32_e32 v37, v36
	s_waitcnt vmcnt(5)
	v_mov_b32_e32 v52, v39
	v_mov_b32_e32 v53, v39
	s_waitcnt vmcnt(4)
	v_mov_b32_e32 v54, v38
	s_waitcnt vmcnt(3)
	v_mov_b32_e32 v41, v40
	s_waitcnt vmcnt(2)
	v_mov_b32_e32 v43, v42
	s_waitcnt vmcnt(0)
	v_mov_b32_e32 v47, v46
	v_mov_b32_e32 v55, v38
	v_mov_b32_e32 v45, v44
	v_mov_b32_e32 v35, v34
	v_mov_b32_e32 v31, v30
	v_mov_b32_e32 v33, v32
	v_mov_b32_e32 v56, v32
	v_mov_b32_e32 v57, v30
	v_mov_b32_e32 v61, v24
	v_and_b32_e32 v250, 15, v195
	v_lshlrev_b32_e32 v250, 9, v250
	v_add_u32_e32 v250, 0x22000, v250
	ds_read_b64 v[204:205], v250
	v_and_b32_e32 v251, 63, v195
	v_lshlrev_b32_e32 v251, 6, v251
	v_add_u32_e32 v251, 0x22000, v251
	ds_read_b64 v[214:215], v251
	ds_read_b64 v[220:221], v251 offset:4096
	v_lshlrev_b32_e32 v250, 3, v195
	v_add_u32_e32 v250, 0x22000, v250
	ds_read_b64 v[232:233], v250
	ds_read_b64 v[240:241], v250 offset:4096
	s_waitcnt lgkmcnt(0)
	v_pk_mul_f32 v[206:207], v[204:205], v[204:205] op_sel:[1,1] op_sel_hi:[1,0]
	v_pk_mul_f32 v[216:217], v[214:215], v[214:215] op_sel:[1,1] op_sel_hi:[1,0]
	v_pk_mul_f32 v[222:223], v[220:221], v[220:221] op_sel:[1,1] op_sel_hi:[1,0]
	v_pk_mul_f32 v[234:235], v[232:233], v[232:233] op_sel:[1,1] op_sel_hi:[1,0]
	v_pk_mul_f32 v[242:243], v[240:241], v[240:241] op_sel:[1,1] op_sel_hi:[1,0]
	v_pk_fma_f32 v[206:207], v[204:205], v[204:205], v[206:207] op_sel:[0,0,0] op_sel_hi:[0,1,1] neg_lo:[0,0,1] neg_hi:[0,0,0]
	v_pk_fma_f32 v[216:217], v[214:215], v[214:215], v[216:217] op_sel:[0,0,0] op_sel_hi:[0,1,1] neg_lo:[0,0,1] neg_hi:[0,0,0]
	v_pk_fma_f32 v[222:223], v[220:221], v[220:221], v[222:223] op_sel:[0,0,0] op_sel_hi:[0,1,1] neg_lo:[0,0,1] neg_hi:[0,0,0]
	v_pk_fma_f32 v[234:235], v[232:233], v[232:233], v[234:235] op_sel:[0,0,0] op_sel_hi:[0,1,1] neg_lo:[0,0,1] neg_hi:[0,0,0]
	v_pk_fma_f32 v[242:243], v[240:241], v[240:241], v[242:243] op_sel:[0,0,0] op_sel_hi:[0,1,1] neg_lo:[0,0,1] neg_hi:[0,0,0]
	v_pk_mul_f32 v[208:209], v[206:207], v[206:207] op_sel:[1,1] op_sel_hi:[1,0]
	v_pk_mul_f32 v[218:219], v[216:217], v[216:217] op_sel:[1,1] op_sel_hi:[1,0]
	v_pk_mul_f32 v[224:225], v[222:223], v[222:223] op_sel:[1,1] op_sel_hi:[1,0]
	v_pk_mul_f32 v[236:237], v[234:235], v[234:235] op_sel:[1,1] op_sel_hi:[1,0]
	v_pk_mul_f32 v[244:245], v[242:243], v[242:243] op_sel:[1,1] op_sel_hi:[1,0]
	v_pk_fma_f32 v[208:209], v[206:207], v[206:207], v[208:209] op_sel:[0,0,0] op_sel_hi:[0,1,1] neg_lo:[0,0,1] neg_hi:[0,0,0]
	v_pk_fma_f32 v[218:219], v[216:217], v[216:217], v[218:219] op_sel:[0,0,0] op_sel_hi:[0,1,1] neg_lo:[0,0,1] neg_hi:[0,0,0]
	v_pk_fma_f32 v[224:225], v[222:223], v[222:223], v[224:225] op_sel:[0,0,0] op_sel_hi:[0,1,1] neg_lo:[0,0,1] neg_hi:[0,0,0]
	v_pk_fma_f32 v[236:237], v[234:235], v[234:235], v[236:237] op_sel:[0,0,0] op_sel_hi:[0,1,1] neg_lo:[0,0,1] neg_hi:[0,0,0]
	v_pk_fma_f32 v[244:245], v[242:243], v[242:243], v[244:245] op_sel:[0,0,0] op_sel_hi:[0,1,1] neg_lo:[0,0,1] neg_hi:[0,0,0]
	v_pk_add_f32 v[250:251], v[204:205], v[204:205] op_sel:[0,1] op_sel_hi:[1,0] neg_lo:[0,0] neg_hi:[0,1]
	s_nop 0
	v_pk_mul_f32 v[210:211], v[250:251], s[16:17] op_sel:[0,0] op_sel_hi:[1,0]
	v_pk_mul_f32 v[212:213], v[250:251], s[16:17] op_sel:[1,0] op_sel_hi:[0,0] neg_lo:[0,0] neg_hi:[1,0]
	.p2align	6

; __device__ __forceinline__ uint4 ntld_u4(const void* p) { const ntu4_t v = __builtin_nontemporal_load((const ntu4_t*)p); return make_uint4(v.x, v.y, v.z, v.w); }
; __device__ __forceinline__ float4 ntld_f4(const void* p) { const ntf4_t v = __builtin_nontemporal_load((const ntf4_t*)p); return make_float4(v.x, v.y, v.z, v.w); }
; __device__ void ph_post(const float* hin_f, const bf16_t* hin_b, const bf16_t* t1, const float* gpost, bf16_t* E, const float* gple, bf16_t* h1b) {
;     ...
;     for (int row = blockIdx.x * 8 + wid; row < T_TOK; row += gridDim.x * 8) {
;         const size_t ro = (size_t)row * DM;
;         uint4 tw[2], ew[2]; float hv[2][8];
; #pragma unroll
;         for (int i = 0; i < 2; ++i) { const int e0 = (lane + 64 * i) * 8; tw[i] = ntld_u4(t1 + ro + e0); ew[i] = ntld_u4(E + ro + e0); }
;         if (hin_b) {
; #pragma unroll
;             for (int i = 0; i < 2; ++i) { const uint4 hw = ntld_u4(hin_b + ro + (lane + 64 * i) * 8); unpack8(hw, hv[i]); }
;         } else {
; #pragma unroll
;             for (int i = 0; i < 2; ++i) { const int e0 = (lane + 64 * i) * 8; const float4 a = ntld_f4(hin_f + ro + e0), b = ntld_f4(hin_f + ro + e0 + 4);
;                 hv[i][0] = a.x; hv[i][1] = a.y; hv[i][2] = a.z; hv[i][3] = a.w; hv[i][4] = b.x; hv[i][5] = b.y; hv[i][6] = b.z; hv[i][7] = b.w; } }
.LBB0_768:
	v_lshl_add_u64 v[4:5], v[54:55], 2, v[48:49]
	global_load_dwordx4 v[8:11], v[4:5], off nt
	global_load_dwordx4 v[12:15], v[4:5], off offset:16 nt
	global_load_dwordx4 v[0:3], v[4:5], off offset:2048 nt
	s_nop 0
	global_load_dwordx4 v[4:7], v[4:5], off offset:2064 nt
	.p2align	6
